# static s_setprio 1 for waves 4-7 (younger half) at entry of the retention-scan and both attention phases, reset at phase end; no per-segment flips
# baseline (speedup 1.0000x reference)
; DI int tid_opaque() { int t = threadIdx.x; asm volatile("" : "+v"(t)); return t; }
; template <bool SWA>
; DI void attn_phase(const Ctx& a, LAS unsigned char* lds) {
;     ...
;     const int tid = tid_opaque(); const int lane = tid & 63, fr = lane & 15, fq = lane >> 4, w = tid >> 6;
;     constexpr int LDQ = SWA ? 1280 : 2048, HD = SWA ? 256 : 1024, NLAT = 2048, NCTX = 128;
;     const int G_ = gridDim.x, vb_ = (G_ % 8 == 0) ? (int)(blockIdx.x % 8) * (G_ / 8) + (int)(blockIdx.x / 8) : (int)blockIdx.x;
;     for (int item = vb_; item < NLAT + NCTX; item += G_) {
;         int b, kvh, hq, qbase, nloc, loc0 = 0;
;         int r = 0, cbk = 0, r0 = 0, cs = 0, rlo = 0, tq0 = 0;
;         const bool lat = item < NLAT;
;         if (lat) {
;             if (!SWA) { const int rp = item & 31; hq = (item >> 5) & 15; b = item >> 9; kvh = hq; r = 2 * rp + (w >> 2); cbk = w & 3; qbase = b * 4096 + r * 64 + 16 * cbk;
;                 r0 = r - 4 < 0 ? 0 : (r - 4 > 56 ? 56 : r - 4); cs = 16 * cbk - 8 < 0 ? 0 : (16 * cbk - 8 > 32 ? 32 : 16 * cbk - 8);
;                 rlo = 2 * rp - 4 < 0 ? 0 : (2 * rp - 4 > 56 ? 56 : 2 * rp - 4); const int rh = 2 * rp - 3 < 0 ? 0 : (2 * rp - 3 > 56 ? 56 : 2 * rp - 3);
;                 nloc = rh + 8 - rlo; loc0 = b * 4096 + rlo * 64; }
;             else { const int tb = item & 127; kvh = (item >> 7) & 3; b = item >> 9; hq = kvh * 4 + (w >> 1); tq0 = 32 * tb + 16 * (w & 1); qbase = b * 4096 + tq0;
;                 int ts = (32 * tb - 128) & ~63; if (ts < 0) ts = 0;
;                 int te = (32 * tb + 159) >> 6; if (te > 63) te = 63;
;                 nloc = te - (ts >> 6) + 1; loc0 = b * 4096 + ts; rlo = ts; }
;         } else {
;             const int i2 = item - NLAT;
;             if (!SWA) { const int hf = i2 & 1; hq = (i2 >> 1) & 15; b = i2 >> 5; kvh = hq; qbase = ML + b * 256 + 128 * hf + 16 * w; }
;             else { const int q8 = i2 & 7; kvh = (i2 >> 3) & 3; b = i2 >> 5; hq = kvh * 4 + (w >> 1); qbase = ML + b * 256 + 32 * q8 + 16 * (w & 1); }
;             nloc = 0;
;         }
;         const int koff = 1024 + kvh * 64, ntile = nloc + 4;
;         int nb_off[8]; float nb_mask[8];
;         if (!SWA) {
; #pragma unroll
;             for (int e = 0; e < 8; ++e) { const int col = cs + 16 * (e >> 2) + 4 * fq + (e & 3), ci = 16 * cbk + fr; const int c0 = ci - 8 < 0 ? 0 : (ci - 8 > 48 ? 48 : ci - 8);
.LBB0_61:
	v_readlane_b32 s0, v254, 57
	v_readlane_b32 s1, v254, 58
	s_mov_b64 s[30:31], -1
	s_and_b64 vcc, exec, s[0:1]
	s_cbranch_vccz .LBB0_192
	v_readlane_b32 s0, v254, 63
	v_readlane_b32 s1, v255, 0
	v_writelane_b32 v255, s16, 32
	s_and_b64 vcc, exec, s[0:1]
	s_nop 0
	v_writelane_b32 v255, s17, 33
	v_writelane_b32 v255, s10, 34
	s_nop 1
	v_writelane_b32 v255, s11, 35
	s_cbranch_vccz .LBB0_123
	v_readlane_b32 s0, v254, 49
	v_readlane_b32 s1, v254, 50
	s_andn2_b64 vcc, exec, s[0:1]
	s_cbranch_vccnz .LBB0_122
	v_readlane_b32 s0, v255, 1
	v_readlane_b32 s1, v255, 2
	s_and_b64 s[2:3], s[0:1], exec
	v_readlane_b32 s0, v255, 3
	s_cselect_b32 s2, s0, s82
	s_waitcnt vmcnt(1)
	v_mov_b32_e32 v0, v200
	s_cmpk_gt_i32 s2, 0x87f
	s_cbranch_scc1 .LBB0_122
	v_ashrrev_i32_e32 v1, 6, v0
	s_waitcnt vmcnt(0)
	v_lshrrev_b32_e32 v4, 4, v0
	v_and_b32_e32 v47, 15, v0
	v_and_b32_e32 v3, 63, v0
	v_bfe_u32 v5, v0, 4, 2
	v_ashrrev_i32_e32 v61, 7, v0
	v_lshlrev_b32_e32 v2, 4, v1
	v_ashrrev_i32_e32 v40, 3, v0
	v_xor_b32_e32 v4, v4, v0
	v_lshl_add_u32 v64, v1, 10, 0
	v_lshrrev_b32_e32 v1, 1, v0
	v_bfe_u32 v6, v0, 1, 3
	v_bfe_u32 v0, v0, 5, 1
	v_lshlrev_b32_e32 v4, 3, v4
	v_bitop3_b32 v7, v5, v1, 7 bitop3:0x78
	v_bitop3_b32 v1, v0, v1, 7 bitop3:0x78
	v_and_b32_e32 v62, 16, v2
	v_lshlrev_b32_e32 v2, 3, v5
	v_cmp_gt_u32_e32 vcc, 16, v3
	v_and_b32_e32 v4, 56, v4
	v_lshlrev_b32_e32 v3, 2, v3
	v_lshlrev_b32_e32 v70, 4, v1
	v_bitop3_b32 v1, v0, v6, 2 bitop3:0x36
	v_lshlrev_b32_e32 v146, 1, v4
	v_lshl_add_u32 v65, v47, 7, 0
	v_lshlrev_b32_e32 v66, 4, v7
	v_bitop3_b32 v7, v5, v6, 4 bitop3:0x36
	v_lshlrev_b32_e32 v46, 2, v5
	v_xor_b32_e32 v68, 64, v3
	v_xor_b32_e32 v69, 0x80, v3
	v_and_b32_e32 v3, 8, v2
	v_lshlrev_b32_e32 v71, 4, v1
	v_bitop3_b32 v1, v0, v6, 4 bitop3:0x36
	v_bitop3_b32 v0, v0, v6, 6 bitop3:0x36
	v_cndmask_b32_e64 v63, 0, 1.0, vcc
	v_ashrrev_i32_e32 v41, 31, v40
	v_lshl_add_u64 v[42:43], s[76:77], 0, v[146:147]
	v_lshl_add_u64 v[44:45], s[50:51], 0, v[146:147]
	v_lshlrev_b32_e32 v67, 4, v7
	v_lshlrev_b32_e32 v72, 4, v1
	v_lshlrev_b32_e32 v73, 4, v0
	v_add_u32_e32 v74, v65, v3
	v_add_u32_e32 v75, 0x100, v40
	v_lshlrev_b32_e32 v146, 1, v2
	v_lshlrev_b32_e32 v48, 1, v4
	v_lshlrev_b32_e32 v50, 1, v46
	v_readfirstlane_b32 s98, v200
	s_nop 3
	s_cmp_ge_u32 s98, 0x100
	s_cbranch_scc0 .Lprio_skip0
	s_setprio 1
.Lprio_skip0:
	s_branch .LBB0_70
.LBB0_66:
	v_readlane_b32 s72, v254, 27
	v_readlane_b32 s73, v254, 28

; DI int tid_opaque() { int t = threadIdx.x; asm volatile("" : "+v"(t)); return t; }
; template <bool SWA>
; DI void attn_phase(const Ctx& a, LAS unsigned char* lds) {
;     ...
;     const int tid = tid_opaque(); const int lane = tid & 63, fr = lane & 15, fq = lane >> 4, w = tid >> 6;
;     constexpr int LDQ = SWA ? 1280 : 2048, HD = SWA ? 256 : 1024, NLAT = 2048, NCTX = 128;
;     const int G_ = gridDim.x, vb_ = (G_ % 8 == 0) ? (int)(blockIdx.x % 8) * (G_ / 8) + (int)(blockIdx.x / 8) : (int)blockIdx.x;
;     for (int item = vb_; item < NLAT + NCTX; item += G_) {
;         int b, kvh, hq, qbase, nloc, loc0 = 0;
;         int r = 0, cbk = 0, r0 = 0, cs = 0, rlo = 0, tq0 = 0;
;         const bool lat = item < NLAT;
;         if (lat) {
;             if (!SWA) { const int rp = item & 31; hq = (item >> 5) & 15; b = item >> 9; kvh = hq; r = 2 * rp + (w >> 2); cbk = w & 3; qbase = b * 4096 + r * 64 + 16 * cbk;
;                 r0 = r - 4 < 0 ? 0 : (r - 4 > 56 ? 56 : r - 4); cs = 16 * cbk - 8 < 0 ? 0 : (16 * cbk - 8 > 32 ? 32 : 16 * cbk - 8);
;                 rlo = 2 * rp - 4 < 0 ? 0 : (2 * rp - 4 > 56 ? 56 : 2 * rp - 4); const int rh = 2 * rp - 3 < 0 ? 0 : (2 * rp - 3 > 56 ? 56 : 2 * rp - 3);
;                 nloc = rh + 8 - rlo; loc0 = b * 4096 + rlo * 64; }
;             else { const int tb = item & 127; kvh = (item >> 7) & 3; b = item >> 9; hq = kvh * 4 + (w >> 1); tq0 = 32 * tb + 16 * (w & 1); qbase = b * 4096 + tq0;
;                 int ts = (32 * tb - 128) & ~63; if (ts < 0) ts = 0;
;                 int te = (32 * tb + 159) >> 6; if (te > 63) te = 63;
;                 nloc = te - (ts >> 6) + 1; loc0 = b * 4096 + ts; rlo = ts; }
;         } else {
;             const int i2 = item - NLAT;
;             if (!SWA) { const int hf = i2 & 1; hq = (i2 >> 1) & 15; b = i2 >> 5; kvh = hq; qbase = ML + b * 256 + 128 * hf + 16 * w; }
;             else { const int q8 = i2 & 7; kvh = (i2 >> 3) & 3; b = i2 >> 5; hq = kvh * 4 + (w >> 1); qbase = ML + b * 256 + 32 * q8 + 16 * (w & 1); }
;             nloc = 0;
;         }
;         const int koff = 1024 + kvh * 64, ntile = nloc + 4;
;         int nb_off[8]; float nb_mask[8];
;         if (!SWA) {
; #pragma unroll
;             for (int e = 0; e < 8; ++e) { const int col = cs + 16 * (e >> 2) + 4 * fq + (e & 3), ci = 16 * cbk + fr; const int c0 = ci - 8 < 0 ? 0 : (ci - 8 > 48 ? 48 : ci - 8);
.LBB0_123:
	s_andn2_b64 vcc, exec, s[30:31]
	s_cbranch_vccnz .LBB0_191
	v_readlane_b32 s0, v255, 1
	v_readlane_b32 s1, v255, 2
	s_and_b64 s[2:3], s[0:1], exec
	v_readlane_b32 s0, v255, 3
	s_cselect_b32 s17, s0, s82
	s_waitcnt vmcnt(0)
	v_mov_b32_e32 v41, v200
	s_cmpk_gt_i32 s17, 0x87f
	s_cbranch_scc1 .LBB0_191
	v_and_b32_e32 v1, 63, v41
	v_lshrrev_b32_e32 v2, 4, v41
	v_bfe_u32 v60, v41, 4, 2
	v_ashrrev_i32_e32 v3, 6, v41
	v_mov_b32_e32 v0, 0x4000
	v_xor_b32_e32 v2, v2, v41
	v_lshlrev_b32_e32 v1, 2, v1
	v_and_b32_e32 v59, 15, v41
	v_lshl_add_u32 v61, v3, 4, v0
	v_lshlrev_b32_e32 v0, 3, v60
	v_lshlrev_b32_e32 v2, 3, v2
	v_xor_b32_e32 v69, 64, v1
	v_xor_b32_e32 v70, 0x80, v1
	v_bfe_u32 v71, v41, 5, 1
	v_lshrrev_b32_e32 v1, 1, v41
	v_bfe_u32 v73, v41, 1, 3
	v_and_b32_e32 v63, 3, v3
	v_and_b32_e32 v2, 56, v2
	v_lshl_add_u32 v66, v3, 10, 0
	v_and_b32_e32 v72, 8, v0
	v_lshl_add_u32 v74, v59, 7, 0
	v_bitop3_b32 v3, v60, v1, 7 bitop3:0x78
	v_bitop3_b32 v4, v60, v73, 4 bitop3:0x36
	v_bitop3_b32 v1, v71, v1, 7 bitop3:0x78
	v_bitop3_b32 v5, v71, v73, 2 bitop3:0x36
	v_bitop3_b32 v6, v71, v73, 4 bitop3:0x36
	v_bitop3_b32 v7, v71, v73, 6 bitop3:0x36
	v_lshlrev_b32_e32 v64, 4, v63
	v_lshlrev_b32_e32 v40, 2, v60
	v_ashrrev_i32_e32 v42, 3, v41
	s_movk_i32 s3, 0x1d1
	v_lshlrev_b32_e32 v146, 1, v2
	v_lshlrev_b32_e32 v3, 4, v3
	v_lshlrev_b32_e32 v4, 4, v4
	v_lshlrev_b32_e32 v1, 4, v1
	v_lshlrev_b32_e32 v5, 4, v5
	v_lshlrev_b32_e32 v6, 4, v6
	v_lshlrev_b32_e32 v7, 4, v7
	v_add_u32_e32 v8, v74, v72
	v_ashrrev_i32_e32 v62, 8, v41
	v_add_u32_e32 v65, -8, v64
	v_cmp_gt_i32_e64 s[40:41], s3, v41
	v_ashrrev_i32_e32 v43, 31, v42
	v_lshl_add_u64 v[44:45], s[76:77], 0, v[146:147]
	v_lshl_add_u32 v67, v41, 2, 0
	v_lshl_add_u64 v[46:47], s[50:51], 0, v[146:147]
	v_or_b32_e32 v68, 4, v60
	v_lshlrev_b32_e32 v48, 1, v0
	v_lshlrev_b32_e32 v146, 1, v2
	v_lshlrev_b32_e32 v50, 1, v40
	v_add_u32_e32 v75, v74, v3
	v_add_u32_e32 v76, v74, v4
	v_add_u32_e32 v77, v8, v1
	v_add_u32_e32 v78, v8, v5
	v_add_u32_e32 v79, v8, v6
	v_add_u32_e32 v80, v8, v7
	v_readfirstlane_b32 s98, v200
	s_nop 3
	s_cmp_ge_u32 s98, 0x100
	s_cbranch_scc0 .Lprio_skip1
	s_setprio 1
.Lprio_skip1:
	s_branch .LBB0_128
.LBB0_126:
	v_mov_b32_e32 v15, 0
	v_mov_b32_e32 v14, v15
	v_mov_b32_e32 v13, v15
	v_mov_b32_e32 v12, v15
	v_mov_b32_e32 v19, v15
	v_mov_b32_e32 v18, v15
	v_mov_b32_e32 v17, v15
	v_mov_b32_e32 v16, v15
	v_mov_b32_e32 v23, v15
	v_mov_b32_e32 v22, v15
	v_mov_b32_e32 v21, v15
	v_mov_b32_e32 v20, v15
	v_mov_b32_e32 v11, v15
	v_mov_b32_e32 v10, v15
	v_mov_b32_e32 v9, v15
	v_mov_b32_e32 v8, v15
	v_mov_b32_e32 v85, v15

; #define LAS __attribute__((address_space(3)))
; DI int tid_opaque() { int t = threadIdx.x; asm volatile("" : "+v"(t)); return t; }
; DI void ret_chain_phase(const Ctx& a, LAS unsigned char* lds) {
;     ...
;     const int tid = tid_opaque(), wid = tid >> 6, lane = tid & 63, fr = lane & 15, fq = lane >> 4;
;     for (int cid = blockIdx.x; cid < 256; cid += gridDim.x) {
;         const int xq = cid & 7, yq = cid >> 3, grp = xq * 4 + (yq >> 3), vs = yq & 7;
;         const int dir = grp & 1, h = (grp >> 1) & 3, b = grp >> 3;
;         const float lg2 = dec[dir * 4 + h];
;         const bf16_t* KT = (const bf16_t*)(a.ws + (dir ? OFF_RKTB : OFF_RKTF));
;         bf16_t* O = (bf16_t*)(a.ws + OFF_ACT) + (dir ? (size_t)MT * 2048 : 0);
;         f32x4 accS[2][4];
; #pragma unroll
;         for (int i = 0; i < 2; ++i)
; #pragma unroll
;             for (int j = 0; j < 4; ++j) accS[i][j] = (f32x4){0.f, 0.f, 0.f, 0.f};
;         for (int i = tid; i < 32768 / 16; i += NTHREADS) *(LAS u32x4*)(lds + RC_SS + i * 16) = (u32x4){0u, 0u, 0u, 0u};
;         const int it = wid & 3, half = wid >> 2;
;         const int icol = 16 * it + fr;
;         const float qdec = __builtin_amdgcn_exp2f(lg2 * (float)(dir ? 64 - icol : icol + 1));
;         const float cdec = __builtin_amdgcn_exp2f(lg2 * 64.f);
;         float wdec[2][4];
; #pragma unroll
;         for (int j2 = 0; j2 < 2; ++j2)
; #pragma unroll
;             for (int r = 0; r < 4; ++r) { const int j = 16 * (2 * half + j2) + 4 * fq + r; const int dd = dir ? (j - icol) : (icol - j); const bool keep = dir ? (dd > 0) : (dd >= 0);
;                 wdec[j2][r] = keep ? __builtin_amdgcn_exp2f(lg2 * (float)dd) : 0.f; }
;         __syncthreads();
;         u32x4 pkt[4], pvt;
;     ...
;         const int qk_src = ((tid >> 5) * 1024 + h * 256 + (((tid & 31) ^ ((tid >> 5) & 15)) * 8)) * 2;
.LBB0_192:
	s_andn2_b64 vcc, exec, s[30:31]
	s_cbranch_vccnz .LBB0_213
	v_readlane_b32 s2, v252, 6
	v_readlane_b32 s3, v252, 7
	s_waitcnt vmcnt(0)
	v_mov_b32_e32 v0, v200
	s_andn2_b64 vcc, exec, s[2:3]
	s_cbranch_vccnz .LBB0_213
	v_readfirstlane_b32 s98, v200
	s_nop 3
	s_cmp_ge_u32 s98, 0x100
	s_cbranch_scc0 .Lprio_skip2
	s_setprio 1
.Lprio_skip2:
	v_ashrrev_i32_e32 v3, 6, v0
	v_and_b32_e32 v120, 15, v0
	v_and_b32_e32 v4, 3, v3
	v_lshl_or_b32 v122, v4, 4, v120
	v_lshrrev_b32_e32 v13, 1, v0
	v_bfe_u32 v121, v0, 4, 2
	v_ashrrev_i32_e32 v5, 8, v0
	v_lshlrev_b32_e32 v12, 7, v122
	s_add_i32 s3, 0, 0x22000
	v_and_b32_e32 v13, 8, v13
	v_lshlrev_b32_e32 v88, 5, v5
	v_lshlrev_b32_e32 v2, 2, v121
	v_lshl_add_u32 v126, v4, 13, 0
	v_add3_u32 v12, s3, v12, v13
	v_mul_i32_i24_e32 v4, 0xffffe800, v4
	s_mov_b32 s3, 0x22000
	v_or_b32_e32 v6, v2, v88
	v_add3_u32 v128, v126, v4, s3
	v_lshlrev_b32_e32 v4, 9, v120
	s_add_i32 s3, 0, 0x10000
	v_add3_u32 v4, s3, v4, v13
	v_or_b32_e32 v13, 1, v6
	v_sub_u32_e32 v132, v13, v122
	v_sub_u32_e32 v133, v122, v13
	v_or_b32_e32 v13, 2, v6
	v_ashrrev_i32_e32 v7, 5, v0
	v_and_b32_e32 v9, 31, v0
	v_sub_u32_e32 v134, v13, v122
	v_sub_u32_e32 v135, v122, v13
	v_or_b32_e32 v13, 3, v6
	s_movk_i32 s2, 0x800
	v_lshlrev_b32_e32 v8, 10, v7
	v_bitop3_b32 v7, v7, v9, 15 bitop3:0x6c
	v_sub_u32_e32 v136, v13, v122
	v_sub_u32_e32 v137, v122, v13
	v_or_b32_e32 v13, 16, v6
	v_cmp_gt_i32_e64 s[40:41], s2, v0
	v_lshl_or_b32 v125, v7, 3, v8
	v_lshlrev_b32_e32 v7, 4, v0
	v_readlane_b32 s0, v255, 6
	s_movk_i32 s2, 0x70
	v_sub_u32_e32 v138, v13, v122
	v_sub_u32_e32 v139, v122, v13
	v_or_b32_e32 v13, 17, v6
	v_and_b32_e32 v146, 0x70, v7
	v_readlane_b32 s1, v255, 7
	v_bitop3_b32 v9, v7, s2, v0 bitop3:0x48
	s_add_i32 s2, 0, 0x20000
	v_sub_u32_e32 v140, v13, v122
	v_sub_u32_e32 v141, v122, v13
	v_or_b32_e32 v13, 18, v6
	v_lshl_or_b32 v15, v5, 1, 1
	s_movk_i32 s20, 0xe800
	v_lshl_add_u64 v[92:93], s[0:1], 0, v[146:147]
	v_lshl_add_u32 v127, v5, 14, 0
	v_sub_u32_e32 v130, v6, v122
	v_sub_u32_e32 v131, v122, v6
	v_sub_u32_e32 v142, v13, v122
	v_sub_u32_e32 v143, v122, v13
	v_or_b32_e32 v6, 19, v6
	v_lshlrev_b32_e32 v13, 2, v5
	v_lshl_add_u32 v163, v15, 13, 0
	v_lshl_add_u32 v166, v5, 12, s2
	v_mul_lo_u32 v5, v15, s20
	s_mov_b32 s0, 0x20000
	v_lshrrev_b32_e32 v1, 4, v0
	v_lshlrev_b32_e32 v8, 10, v3
	v_sub_u32_e32 v144, v6, v122
	v_sub_u32_e32 v145, v122, v6
	v_add_u32_e32 v6, 0x200, v0
	v_add3_u32 v167, v163, v5, s0
	v_lshl_add_u32 v168, v3, 12, s74
	v_lshlrev_b32_e32 v5, 2, v3
	v_lshl_or_b32 v3, v3, 1, 1
	v_bfe_u32 v1, v1, 1, 1
	v_bfe_u32 v14, v0, 1, 3
	v_ashrrev_i32_e32 v94, 3, v6
	v_add_u32_e32 v6, 0x400, v0
	v_lshlrev_b32_e32 v16, 1, v15
	v_lshl_add_u32 v169, v3, 11, s74
	v_lshlrev_b32_e32 v3, 1, v3
	v_ashrrev_i32_e32 v90, 3, v0
	v_ashrrev_i32_e32 v96, 3, v6
	v_add_u32_e32 v6, 0x600, v0
	v_bitop3_b32 v13, v1, v14, v13 bitop3:0x36
	v_bitop3_b32 v14, v16, v14, v1 bitop3:0x36
	v_bitop3_b32 v5, v1, v120, v5 bitop3:0x36
	v_bitop3_b32 v1, v3, v120, v1 bitop3:0x36
	v_add_u32_e32 v10, s74, v9
	v_lshl_add_u32 v11, v90, 7, s2
	v_ashrrev_i32_e32 v98, 3, v6
	v_and_b32_e32 v6, 0xffffff80, v7
	v_lshlrev_b32_e32 v13, 4, v13
	v_lshlrev_b32_e32 v14, 4, v14
	v_lshlrev_b32_e32 v100, 4, v15
	v_lshlrev_b32_e32 v5, 4, v5
	v_lshlrev_b32_e32 v1, 4, v1
	v_sub_u32_e32 v123, 64, v122
	v_add_u32_e32 v124, 1, v122
	v_ashrrev_i32_e32 v91, 31, v90
	v_or_b32_e32 v129, 4, v121
	v_ashrrev_i32_e32 v95, 31, v94
	v_ashrrev_i32_e32 v97, 31, v96
	v_ashrrev_i32_e32 v99, 31, v98
	v_or_b32_e32 v157, 8, v121
	v_or_b32_e32 v158, 12, v121
	v_or_b32_e32 v159, 16, v121
	v_or_b32_e32 v160, 20, v121
	v_or_b32_e32 v161, 24, v121
	v_or_b32_e32 v162, 28, v121
	v_add_u32_e32 v164, 0x10000, v127
	v_add_u32_e32 v165, 0x12000, v127
	v_ashrrev_i32_e32 v89, 31, v88
	v_ashrrev_i32_e32 v101, 31, v100
	v_lshl_add_u64 v[102:103], s[38:39], 0, v[146:147]
	v_add_u32_e32 v170, 0xfffffe00, v0
	v_add_u32_e32 v171, s3, v7
	v_lshlrev_b32_e32 v146, 1, v2
	v_add_u32_e32 v172, 0, v8
	v_add_u32_e32 v173, v10, v6
	v_add_u32_e32 v174, v11, v9
	v_add_u32_e32 v175, v12, v13
	v_add_u32_e32 v176, v12, v14
	v_add_u32_e32 v177, v4, v5
	v_add_u32_e32 v178, v4, v1
	s_mov_b32 s3, s82

; __device__ __forceinline__ unsigned xb_add(unsigned* p, unsigned v) { return __hip_atomic_fetch_add(p, v, __ATOMIC_RELAXED, __HIP_MEMORY_SCOPE_AGENT); }
; __device__ __forceinline__ void xcd_barrier(const XcdBarrier& b) {
;     asm volatile("s_waitcnt vmcnt(0)" ::: "memory");
;     __syncthreads();
;     if (threadIdx.x == 0) {
;         unsigned* bar = b.bar;
;         __builtin_amdgcn_s_waitcnt(0);
;         unsigned nloc = b.st[0], nx = b.st[1];
;         if (nloc == 0u) { xcd_barrier_complete(bar, b.x, nloc, nx); b.st[0] = nloc; b.st[1] = nx; }
;         const unsigned old = xb_add(&bar[XB_XSUB(b.x)], 1u);
; __global__ void __launch_bounds__(NTHREADS) mega(Args a) {
;     ...
;         if (ph + 1 < a.ph_hi) { if (ph == 0) cg::this_grid().sync(); else xcd_barrier(xbar); }
.LBB0_603:
	s_setprio 0
	s_add_i32 s25, s90, 1
	s_cmp_ge_i32 s25, s91
	s_cbranch_scc1 .LBB0_7
	v_readlane_b32 s0, v254, 46
	v_readlane_b32 s1, v254, 47
	s_mov_b64 s[2:3], -1
	s_and_b64 vcc, exec, s[0:1]
	s_mov_b64 s[52:53], 0x8000
	s_mov_b64 s[68:69], 0x18000
	s_waitcnt vmcnt(0)
	v_readlane_b32 s0, v252, 2
	v_readlane_b32 s1, v252, 3
	s_waitcnt vmcnt(0) lgkmcnt(0)
	s_barrier
	s_and_saveexec_b64 s[2:3], s[0:1]
	s_cbranch_execz .LBB0_657
	s_add_i32 s36, 0, 0x24000
	v_mov_b32_e32 v0, s36
	s_waitcnt vmcnt(0) expcnt(0) lgkmcnt(0)
	ds_read_b32 v2, v0
	v_readlane_b32 s1, v253, 43
	s_waitcnt lgkmcnt(0)
	v_cmp_ne_u32_e32 vcc, 0, v2
	v_mov_b32_e32 v0, s1
	ds_read_b32 v0, v0
	s_cbranch_vccnz .LBB0_621
	s_load_dwordx2 s[20:21], s[60:61], 0x4
	s_mov_b32 s38, 1
	s_waitcnt lgkmcnt(0)
	s_mul_i32 s37, s20, s54
	s_mul_i32 s37, s37, s21
	s_branch .LBB0_609
